# attention row-max tree reordered: first score chain reduced under the last QK MFMA
# baseline (speedup 1.0000x reference)
.LBB0_476:
	v_max3_f32 v78, v50, v51, v52
	v_max3_f32 v124, v53, v54, v55
	v_max3_f32 v78, v78, v56, v57
	v_max3_f32 v124, v124, v58, v59
	v_max3_f32 v78, v78, v60, v61
	v_max3_f32 v124, v124, v62, v63
	v_max3_f32 v78, v78, v64, v65
	v_max3_f32 v124, v124, v34, v35
	v_max3_f32 v78, v78, v36, v37
	v_max3_f32 v124, v124, v38, v39
	v_max3_f32 v78, v78, v40, v41
	v_max3_f32 v124, v124, v42, v43
	v_max3_f32 v78, v78, v44, v45
	v_max3_f32 v124, v124, v46, v47
	v_max3_f32 v78, v78, v48, v49
	v_max_f32_e32 v78, v78, v124
	v_mov_b32_e32 v124, v78
	s_nop 1
	v_permlane32_swap_b32_e32 v78, v124
	v_max_f32_e32 v78, v78, v124
	v_cmp_lt_f32_e32 vcc, s72, v78
	s_cbranch_vccz .LBB0_464
	s_nop 1
	v_cndmask_b32_e32 v78, 0, v78, vcc
	v_exp_f32_e64 v124, -v78
	v_pk_add_f32 v[50:51], v[50:51], v[78:79] op_sel_hi:[1,0] neg_lo:[0,1] neg_hi:[0,1]
	v_pk_add_f32 v[34:35], v[34:35], v[78:79] op_sel_hi:[1,0] neg_lo:[0,1] neg_hi:[0,1]
	v_pk_add_f32 v[52:53], v[52:53], v[78:79] op_sel_hi:[1,0] neg_lo:[0,1] neg_hi:[0,1]
	v_pk_add_f32 v[36:37], v[36:37], v[78:79] op_sel_hi:[1,0] neg_lo:[0,1] neg_hi:[0,1]
	v_pk_add_f32 v[54:55], v[54:55], v[78:79] op_sel_hi:[1,0] neg_lo:[0,1] neg_hi:[0,1]
	v_pk_add_f32 v[38:39], v[38:39], v[78:79] op_sel_hi:[1,0] neg_lo:[0,1] neg_hi:[0,1]
	v_pk_add_f32 v[56:57], v[56:57], v[78:79] op_sel_hi:[1,0] neg_lo:[0,1] neg_hi:[0,1]
	v_pk_add_f32 v[40:41], v[40:41], v[78:79] op_sel_hi:[1,0] neg_lo:[0,1] neg_hi:[0,1]
	v_pk_add_f32 v[58:59], v[58:59], v[78:79] op_sel_hi:[1,0] neg_lo:[0,1] neg_hi:[0,1]
	v_pk_add_f32 v[42:43], v[42:43], v[78:79] op_sel_hi:[1,0] neg_lo:[0,1] neg_hi:[0,1]
	v_pk_add_f32 v[60:61], v[60:61], v[78:79] op_sel_hi:[1,0] neg_lo:[0,1] neg_hi:[0,1]
	v_pk_add_f32 v[44:45], v[44:45], v[78:79] op_sel_hi:[1,0] neg_lo:[0,1] neg_hi:[0,1]
	v_pk_add_f32 v[62:63], v[62:63], v[78:79] op_sel_hi:[1,0] neg_lo:[0,1] neg_hi:[0,1]
	v_pk_add_f32 v[46:47], v[46:47], v[78:79] op_sel_hi:[1,0] neg_lo:[0,1] neg_hi:[0,1]
	v_pk_add_f32 v[64:65], v[64:65], v[78:79] op_sel_hi:[1,0] neg_lo:[0,1] neg_hi:[0,1]
	v_pk_add_f32 v[48:49], v[48:49], v[78:79] op_sel_hi:[1,0] neg_lo:[0,1] neg_hi:[0,1]
	v_pk_mul_f32 v[16:17], v[16:17], v[124:125] op_sel_hi:[1,0]
	v_pk_mul_f32 v[14:15], v[14:15], v[124:125] op_sel_hi:[1,0]
	v_pk_mul_f32 v[12:13], v[12:13], v[124:125] op_sel_hi:[1,0]
	v_pk_mul_f32 v[10:11], v[10:11], v[124:125] op_sel_hi:[1,0]
	v_pk_mul_f32 v[8:9], v[8:9], v[124:125] op_sel_hi:[1,0]
	v_pk_mul_f32 v[6:7], v[6:7], v[124:125] op_sel_hi:[1,0]
	v_pk_mul_f32 v[4:5], v[4:5], v[124:125] op_sel_hi:[1,0]
	v_pk_mul_f32 v[2:3], v[2:3], v[124:125] op_sel_hi:[1,0]
	v_pk_mul_f32 v[32:33], v[32:33], v[124:125] op_sel_hi:[1,0]
	v_pk_mul_f32 v[30:31], v[30:31], v[124:125] op_sel_hi:[1,0]
	v_pk_mul_f32 v[28:29], v[28:29], v[124:125] op_sel_hi:[1,0]
	v_pk_mul_f32 v[26:27], v[26:27], v[124:125] op_sel_hi:[1,0]
	v_pk_mul_f32 v[24:25], v[24:25], v[124:125] op_sel_hi:[1,0]
	v_pk_mul_f32 v[22:23], v[22:23], v[124:125] op_sel_hi:[1,0]
	v_pk_mul_f32 v[20:21], v[20:21], v[124:125] op_sel_hi:[1,0]
	v_pk_mul_f32 v[18:19], v[18:19], v[124:125] op_sel_hi:[1,0]
	v_add_f32_e32 v153, v153, v78
	v_mul_f32_e32 v79, v79, v124
	s_branch .LBB0_464
